# back-edge rotation of FFN-in and mixer-in K-loops: next-iteration SALU address math moved into the last MFMA block's shadow, 2 instrs left after the loop-back barrier
# baseline (speedup 1.0000x reference)
; #define PG8_STAGE(bufoff, gbase, voff) do { _Pragma("unroll") for (int _i = 0; _i < 2; ++_i) \
;         __builtin_amdgcn_global_load_lds((const unsigned*)((const char*)(gbase) + (voff)[_i]), (LAS unsigned*)(lds + (bufoff) + ldsw + _i * 8192), 16, 0, 0); } while (0)
; #define PG8_LDA(dst, b, h) do { _Pragma("unroll") for (int m = 0; m < 4; ++m) _Pragma("unroll") for (int k = 0; k < 2; ++k) dst[m][k] = *(const LAS bf16x8*)(lds + PG8_SA(b, h) + aoff + m * 2048 + k * 1024); } while (0)
; #define PG8_LDB(dst, b, h) do { _Pragma("unroll") for (int n = 0; n < 2; ++n) _Pragma("unroll") for (int k = 0; k < 2; ++k) dst[n][k] = *(const LAS bf16x8*)(lds + PG8_SB(b, h) + boff + n * 2048 + k * 1024); } while (0)
; #define PG8_MMA(ai, bj, At, Bt) do { __builtin_amdgcn_s_setprio(1); _Pragma("unroll") for (int m = 0; m < 4; ++m) _Pragma("unroll") for (int n = 0; n < 2; ++n) _Pragma("unroll") for (int k = 0; k < 2; ++k) \
;         acc[ai][bj][m][n] = __builtin_amdgcn_mfma_f32_16x16x32_bf16(Bt[n][k], At[m][k], acc[ai][bj][m][n], 0, 0, 0); __builtin_amdgcn_s_setprio(0); } while (0)
; #define PG8_WAIT_V(n) asm volatile("s_waitcnt vmcnt(" #n ")" ::: "memory")
; #define PG8_BAR __builtin_amdgcn_s_barrier()
; template <class Epi, class Sched, int KC, bool ALIGN_EPI = false, bool SP2 = false, bool ATILED = false>
; __device__ __forceinline__ void gemm_phase(LAS unsigned char* lds, const Gemm g, const Sched& S, const Epi& E, int wave_s) {
;     ...
;         for (int t = 0; t < nt; t += 2) {
;             const bool last = (t == nt - 2);
;             const char* a1 = cA + PG8_AOFF(t + 1);
;             const char* a2 = last ? nA : cA + PG8_AOFF(t + 2); const char* b2 = last ? nB : cB + (size_t)(t + 2) * kstep;
;             const char* a3 = a2 + kstep; const char* b3 = b2 + kstep;
;             if (last && has_next) S.a_ready(nxt);
;             if constexpr (SP2) {
;             PG8_LDB(B0, 0, 0); PG8_LDB(B1, 0, 1); PG8_SCHED; PG8_LDA(At, 0, 0); PG8_STAGE(PG8_SA(1, 1), a1 + hstepA, voffA);
;             PG8_WAIT_V(8); PG8_WAIT_L(0); PG8_BAR; PG8_MMA(0, 0, At, B0); PG8_MMA(0, 1, At, B1); PG8_BAR; PG8_SCHED;
;             PG8_LDA(At, 0, 1); PG8_STAGE(PG8_SB(0, 0), b2, voffB); PG8_STAGE(PG8_SB(0, 1), b2 + hstepB, voffB); PG8_STAGE(PG8_SA(0, 0), a2, voffA);
;             PG8_WAIT_V(8); PG8_WAIT_L(0); PG8_BAR; PG8_MMA(1, 0, At, B0); PG8_MMA(1, 1, At, B1); PG8_BAR; PG8_SCHED;
.LrotLBB0_233:
	ds_read_b128 v[152:155], v139
	ds_read_b128 v[156:159], v139 offset:1024
	ds_read_b128 v[168:171], v139 offset:2048
	ds_read_b128 v[172:175], v139 offset:3072
	v_add_u32_e32 v139, s63, v163
	ds_read_b128 v[176:179], v139
	ds_read_b128 v[180:183], v139 offset:1024
	ds_read_b128 v[184:187], v139 offset:2048
	ds_read_b128 v[188:191], v139 offset:3072
	s_add_u32 s59, s26, s59
	s_addc_u32 s61, s27, 0
	s_add_u32 s60, s59, 0x10080
	s_addc_u32 s61, s61, 0
	s_add_i32 m0, s44, 0xc000
	ds_read_b128 v[198:201], v166
	ds_read_b128 v[202:205], v166 offset:1024
	ds_read_b128 v[206:209], v166 offset:2048
	ds_read_b128 v[210:213], v166 offset:3072
	ds_read_b128 v[214:217], v166 offset:4096
	ds_read_b128 v[218:221], v166 offset:5120
	ds_read_b128 v[222:225], v166 offset:6144
	ds_read_b128 v[226:229], v166 offset:7168
	global_load_lds_dwordx4 v136, s[60:61]
	s_add_i32 m0, s44, 0xe000
	s_nop 0
	global_load_lds_dwordx4 v132, s[60:61]
	s_waitcnt vmcnt(8)
	s_waitcnt lgkmcnt(0)
	s_barrier
	v_mfma_f32_16x16x32_bf16 v[122:125], v[152:155], v[198:201], v[122:125]
	v_mfma_f32_16x16x32_bf16 v[114:117], v[168:171], v[198:201], v[114:117]
	v_mfma_f32_16x16x32_bf16 v[106:109], v[152:155], v[206:209], v[106:109]
	v_mfma_f32_16x16x32_bf16 v[98:101], v[168:171], v[206:209], v[98:101]
	v_mfma_f32_16x16x32_bf16 v[90:93], v[152:155], v[214:217], v[90:93]
	v_mfma_f32_16x16x32_bf16 v[82:85], v[168:171], v[214:217], v[82:85]
	v_mfma_f32_16x16x32_bf16 v[74:77], v[152:155], v[222:225], v[74:77]
	v_mfma_f32_16x16x32_bf16 v[66:69], v[168:171], v[222:225], v[66:69]
	v_mfma_f32_16x16x32_bf16 v[122:125], v[156:159], v[202:205], v[122:125]
	v_mfma_f32_16x16x32_bf16 v[114:117], v[172:175], v[202:205], v[114:117]
	v_mfma_f32_16x16x32_bf16 v[106:109], v[156:159], v[210:213], v[106:109]
	v_mfma_f32_16x16x32_bf16 v[98:101], v[172:175], v[210:213], v[98:101]
	v_mfma_f32_16x16x32_bf16 v[90:93], v[156:159], v[218:221], v[90:93]
	v_mfma_f32_16x16x32_bf16 v[82:85], v[172:175], v[218:221], v[82:85]
	v_mfma_f32_16x16x32_bf16 v[74:77], v[156:159], v[226:229], v[74:77]
	v_mfma_f32_16x16x32_bf16 v[66:69], v[172:175], v[226:229], v[66:69]
	v_mfma_f32_16x16x32_bf16 v[126:129], v[176:179], v[198:201], v[126:129]
	v_mfma_f32_16x16x32_bf16 v[118:121], v[184:187], v[198:201], v[118:121]
	v_mfma_f32_16x16x32_bf16 v[110:113], v[176:179], v[206:209], v[110:113]
	v_mfma_f32_16x16x32_bf16 v[102:105], v[184:187], v[206:209], v[102:105]
	v_mfma_f32_16x16x32_bf16 v[94:97], v[176:179], v[214:217], v[94:97]
	v_mfma_f32_16x16x32_bf16 v[86:89], v[184:187], v[214:217], v[86:89]
	v_mfma_f32_16x16x32_bf16 v[78:81], v[176:179], v[222:225], v[78:81]
	v_mfma_f32_16x16x32_bf16 v[70:73], v[184:187], v[222:225], v[70:73]
	v_mfma_f32_16x16x32_bf16 v[126:129], v[180:183], v[202:205], v[126:129]
	v_mfma_f32_16x16x32_bf16 v[118:121], v[188:191], v[202:205], v[118:121]
	v_mfma_f32_16x16x32_bf16 v[110:113], v[180:183], v[210:213], v[110:113]
	v_mfma_f32_16x16x32_bf16 v[102:105], v[188:191], v[210:213], v[102:105]
	v_mfma_f32_16x16x32_bf16 v[94:97], v[180:183], v[218:221], v[94:97]
	v_mfma_f32_16x16x32_bf16 v[86:89], v[188:191], v[218:221], v[86:89]
	v_mfma_f32_16x16x32_bf16 v[78:81], v[180:183], v[226:229], v[78:81]
	v_mfma_f32_16x16x32_bf16 v[70:73], v[188:191], v[226:229], v[70:73]
	s_barrier
	s_add_u32 s100, s34, 0x80
	s_addc_u32 s101, s35, 0
	s_add_i32 s59, s62, s38
	s_mov_b32 m0, s59
	ds_read_b128 v[198:201], v166 offset:16384
	ds_read_b128 v[202:205], v166 offset:17408
	ds_read_b128 v[206:209], v166 offset:18432
	ds_read_b128 v[210:213], v166 offset:19456
	ds_read_b128 v[214:217], v166 offset:20480
	ds_read_b128 v[218:221], v166 offset:21504
	ds_read_b128 v[222:225], v166 offset:22528
	ds_read_b128 v[226:229], v166 offset:23552
	global_load_lds_dwordx4 v134, s[28:29]
	s_add_i32 m0, s59, 0x2000
	s_add_u32 s60, s28, 0x80000
	s_addc_u32 s61, s29, 0
	s_add_i32 s59, s63, s38
	global_load_lds_dwordx4 v130, s[28:29]
	s_mov_b32 m0, s59
	s_nop 0
	global_load_lds_dwordx4 v134, s[60:61]
	s_add_i32 m0, s59, 0x2000
	s_nop 0
	global_load_lds_dwordx4 v130, s[60:61]
	s_mov_b32 m0, s44
	s_nop 0
	global_load_lds_dwordx4 v136, s[34:35]
	s_mov_b32 m0, s45
	s_nop 0
	global_load_lds_dwordx4 v132, s[34:35]
	s_waitcnt vmcnt(8)
	s_waitcnt lgkmcnt(0)
	s_barrier
	v_mfma_f32_16x16x32_bf16 v[58:61], v[152:155], v[198:201], v[58:61]
	v_mfma_f32_16x16x32_bf16 v[50:53], v[168:171], v[198:201], v[50:53]
	v_mfma_f32_16x16x32_bf16 v[42:45], v[152:155], v[206:209], v[42:45]
	v_mfma_f32_16x16x32_bf16 v[34:37], v[168:171], v[206:209], v[34:37]
	v_mfma_f32_16x16x32_bf16 v[26:29], v[152:155], v[214:217], v[26:29]
	v_mfma_f32_16x16x32_bf16 v[18:21], v[168:171], v[214:217], v[18:21]
	v_mfma_f32_16x16x32_bf16 v[10:13], v[152:155], v[222:225], v[10:13]
	v_mfma_f32_16x16x32_bf16 v[6:9], v[168:171], v[222:225], v[6:9]
	v_mfma_f32_16x16x32_bf16 v[58:61], v[156:159], v[202:205], v[58:61]
	v_mfma_f32_16x16x32_bf16 v[50:53], v[172:175], v[202:205], v[50:53]
	v_mfma_f32_16x16x32_bf16 v[42:45], v[156:159], v[210:213], v[42:45]
	v_mfma_f32_16x16x32_bf16 v[34:37], v[172:175], v[210:213], v[34:37]
	v_mfma_f32_16x16x32_bf16 v[26:29], v[156:159], v[218:221], v[26:29]
	v_mfma_f32_16x16x32_bf16 v[18:21], v[172:175], v[218:221], v[18:21]
	v_mfma_f32_16x16x32_bf16 v[10:13], v[156:159], v[226:229], v[10:13]
	v_mfma_f32_16x16x32_bf16 v[6:9], v[172:175], v[226:229], v[6:9]
	v_mfma_f32_16x16x32_bf16 v[62:65], v[176:179], v[198:201], v[62:65]
	v_mfma_f32_16x16x32_bf16 v[54:57], v[184:187], v[198:201], v[54:57]
	v_mfma_f32_16x16x32_bf16 v[46:49], v[176:179], v[206:209], v[46:49]
	v_mfma_f32_16x16x32_bf16 v[38:41], v[184:187], v[206:209], v[38:41]
	v_mfma_f32_16x16x32_bf16 v[30:33], v[176:179], v[214:217], v[30:33]
	v_mfma_f32_16x16x32_bf16 v[22:25], v[184:187], v[214:217], v[22:25]
	v_mfma_f32_16x16x32_bf16 v[14:17], v[176:179], v[222:225], v[14:17]
	v_mfma_f32_16x16x32_bf16 v[2:5], v[184:187], v[222:225], v[2:5]
	v_mfma_f32_16x16x32_bf16 v[62:65], v[180:183], v[202:205], v[62:65]
	v_mfma_f32_16x16x32_bf16 v[54:57], v[188:191], v[202:205], v[54:57]
	v_mfma_f32_16x16x32_bf16 v[46:49], v[180:183], v[210:213], v[46:49]
	v_mfma_f32_16x16x32_bf16 v[38:41], v[188:191], v[210:213], v[38:41]
	v_mfma_f32_16x16x32_bf16 v[30:33], v[180:183], v[218:221], v[30:33]
	v_mfma_f32_16x16x32_bf16 v[22:25], v[188:191], v[218:221], v[22:25]
	v_mfma_f32_16x16x32_bf16 v[14:17], v[180:183], v[226:229], v[14:17]
	v_mfma_f32_16x16x32_bf16 v[2:5], v[188:191], v[226:229], v[2:5]
	s_barrier
; #define PG8_STAGE(bufoff, gbase, voff) do { _Pragma("unroll") for (int _i = 0; _i < 2; ++_i) \
;         __builtin_amdgcn_global_load_lds((const unsigned*)((const char*)(gbase) + (voff)[_i]), (LAS unsigned*)(lds + (bufoff) + ldsw + _i * 8192), 16, 0, 0); } while (0)
; #define PG8_LDA(dst, b, h) do { _Pragma("unroll") for (int m = 0; m < 4; ++m) _Pragma("unroll") for (int k = 0; k < 2; ++k) dst[m][k] = *(const LAS bf16x8*)(lds + PG8_SA(b, h) + aoff + m * 2048 + k * 1024); } while (0)
; #define PG8_LDB(dst, b, h) do { _Pragma("unroll") for (int n = 0; n < 2; ++n) _Pragma("unroll") for (int k = 0; k < 2; ++k) dst[n][k] = *(const LAS bf16x8*)(lds + PG8_SB(b, h) + boff + n * 2048 + k * 1024); } while (0)
; #define PG8_MMA(ai, bj, At, Bt) do { __builtin_amdgcn_s_setprio(1); _Pragma("unroll") for (int m = 0; m < 4; ++m) _Pragma("unroll") for (int n = 0; n < 2; ++n) _Pragma("unroll") for (int k = 0; k < 2; ++k) \
;         acc[ai][bj][m][n] = __builtin_amdgcn_mfma_f32_16x16x32_bf16(Bt[n][k], At[m][k], acc[ai][bj][m][n], 0, 0, 0); __builtin_amdgcn_s_setprio(0); } while (0)
; #define PG8_WAIT_V(n) asm volatile("s_waitcnt vmcnt(" #n ")" ::: "memory")
; #define PG8_WAIT_L(n) asm volatile("s_waitcnt lgkmcnt(" #n ")" ::: "memory")
; #define PG8_BAR __builtin_amdgcn_s_barrier()
; #define PG8_SCHED __builtin_amdgcn_sched_barrier(0)
; template <class Epi, class Sched, int KC, bool ALIGN_EPI = false, bool SP2 = false, bool ATILED = false>
; __device__ __forceinline__ void gemm_phase(LAS unsigned char* lds, const Gemm g, const Sched& S, const Epi& E, int wave_s) {
;     ...
;             PG8_LDB(B0, 1, 0); PG8_LDB(B1, 1, 1); PG8_SCHED; PG8_LDA(At, 1, 0); PG8_STAGE(PG8_SA(0, 1), a2 + hstepA, voffA);
;             PG8_WAIT_V(8); PG8_WAIT_L(0); PG8_BAR; PG8_MMA(0, 0, At, B0); PG8_MMA(0, 1, At, B1); PG8_BAR; PG8_SCHED;
	s_add_i32 s59, 0, 0x18000
	v_add_u32_e32 v139, s59, v163
	s_add_i32 s60, 0, 0x1c000
	ds_read_b128 v[152:155], v139
	ds_read_b128 v[156:159], v139 offset:1024
	ds_read_b128 v[168:171], v139 offset:2048
	ds_read_b128 v[172:175], v139 offset:3072
	v_add_u32_e32 v139, s60, v163
	ds_read_b128 v[176:179], v139
	ds_read_b128 v[180:183], v139 offset:1024
	ds_read_b128 v[184:187], v139 offset:2048
	ds_read_b128 v[188:191], v139 offset:3072
	s_add_u32 s34, s34, 0x10000
	s_addc_u32 s35, s35, 0
	s_mov_b32 m0, s46
	ds_read_b128 v[198:201], v166 offset:32768
	ds_read_b128 v[202:205], v166 offset:33792
	ds_read_b128 v[206:209], v166 offset:34816
	ds_read_b128 v[210:213], v166 offset:35840
	ds_read_b128 v[214:217], v166 offset:36864
	ds_read_b128 v[218:221], v166 offset:37888
	ds_read_b128 v[222:225], v166 offset:38912
	ds_read_b128 v[226:229], v166 offset:39936
	global_load_lds_dwordx4 v136, s[34:35]
	s_mov_b32 m0, s47
	s_nop 0
	global_load_lds_dwordx4 v132, s[34:35]
	s_waitcnt vmcnt(8)
	s_waitcnt lgkmcnt(0)
	s_barrier
	v_mfma_f32_16x16x32_bf16 v[122:125], v[152:155], v[198:201], v[122:125]
	v_mfma_f32_16x16x32_bf16 v[114:117], v[168:171], v[198:201], v[114:117]
	v_mfma_f32_16x16x32_bf16 v[106:109], v[152:155], v[206:209], v[106:109]
	v_mfma_f32_16x16x32_bf16 v[98:101], v[168:171], v[206:209], v[98:101]
	v_mfma_f32_16x16x32_bf16 v[90:93], v[152:155], v[214:217], v[90:93]
	v_mfma_f32_16x16x32_bf16 v[82:85], v[168:171], v[214:217], v[82:85]
	v_mfma_f32_16x16x32_bf16 v[74:77], v[152:155], v[222:225], v[74:77]
	v_mfma_f32_16x16x32_bf16 v[66:69], v[168:171], v[222:225], v[66:69]
	v_mfma_f32_16x16x32_bf16 v[122:125], v[156:159], v[202:205], v[122:125]
	v_mfma_f32_16x16x32_bf16 v[114:117], v[172:175], v[202:205], v[114:117]
	v_mfma_f32_16x16x32_bf16 v[106:109], v[156:159], v[210:213], v[106:109]
	v_mfma_f32_16x16x32_bf16 v[98:101], v[172:175], v[210:213], v[98:101]
	v_mfma_f32_16x16x32_bf16 v[90:93], v[156:159], v[218:221], v[90:93]
	v_mfma_f32_16x16x32_bf16 v[82:85], v[172:175], v[218:221], v[82:85]
	v_mfma_f32_16x16x32_bf16 v[74:77], v[156:159], v[226:229], v[74:77]
	v_mfma_f32_16x16x32_bf16 v[66:69], v[172:175], v[226:229], v[66:69]
	v_mfma_f32_16x16x32_bf16 v[126:129], v[176:179], v[198:201], v[126:129]
	v_mfma_f32_16x16x32_bf16 v[118:121], v[184:187], v[198:201], v[118:121]
	v_mfma_f32_16x16x32_bf16 v[110:113], v[176:179], v[206:209], v[110:113]
	v_mfma_f32_16x16x32_bf16 v[102:105], v[184:187], v[206:209], v[102:105]
	v_mfma_f32_16x16x32_bf16 v[94:97], v[176:179], v[214:217], v[94:97]
	v_mfma_f32_16x16x32_bf16 v[86:89], v[184:187], v[214:217], v[86:89]
	v_mfma_f32_16x16x32_bf16 v[78:81], v[176:179], v[222:225], v[78:81]
	v_mfma_f32_16x16x32_bf16 v[70:73], v[184:187], v[222:225], v[70:73]
	v_mfma_f32_16x16x32_bf16 v[126:129], v[180:183], v[202:205], v[126:129]
	v_mfma_f32_16x16x32_bf16 v[118:121], v[188:191], v[202:205], v[118:121]
	v_mfma_f32_16x16x32_bf16 v[110:113], v[180:183], v[210:213], v[110:113]
	v_mfma_f32_16x16x32_bf16 v[102:105], v[188:191], v[210:213], v[102:105]
	v_mfma_f32_16x16x32_bf16 v[94:97], v[180:183], v[218:221], v[94:97]
	v_mfma_f32_16x16x32_bf16 v[86:89], v[188:191], v[218:221], v[86:89]
	v_mfma_f32_16x16x32_bf16 v[78:81], v[180:183], v[226:229], v[78:81]
	v_mfma_f32_16x16x32_bf16 v[70:73], v[188:191], v[226:229], v[70:73]
	s_barrier
; #define PG8_STAGE(bufoff, gbase, voff) do { _Pragma("unroll") for (int _i = 0; _i < 2; ++_i) \
;         __builtin_amdgcn_global_load_lds((const unsigned*)((const char*)(gbase) + (voff)[_i]), (LAS unsigned*)(lds + (bufoff) + ldsw + _i * 8192), 16, 0, 0); } while (0)
; #define PG8_LDA(dst, b, h) do { _Pragma("unroll") for (int m = 0; m < 4; ++m) _Pragma("unroll") for (int k = 0; k < 2; ++k) dst[m][k] = *(const LAS bf16x8*)(lds + PG8_SA(b, h) + aoff + m * 2048 + k * 1024); } while (0)
; #define PG8_MMA(ai, bj, At, Bt) do { __builtin_amdgcn_s_setprio(1); _Pragma("unroll") for (int m = 0; m < 4; ++m) _Pragma("unroll") for (int n = 0; n < 2; ++n) _Pragma("unroll") for (int k = 0; k < 2; ++k) \
;         acc[ai][bj][m][n] = __builtin_amdgcn_mfma_f32_16x16x32_bf16(Bt[n][k], At[m][k], acc[ai][bj][m][n], 0, 0, 0); __builtin_amdgcn_s_setprio(0); } while (0)
; #define PG8_WAIT_V(n) asm volatile("s_waitcnt vmcnt(" #n ")" ::: "memory")
; #define PG8_WAIT_L(n) asm volatile("s_waitcnt lgkmcnt(" #n ")" ::: "memory")
; #define PG8_BAR __builtin_amdgcn_s_barrier()
; #define PG8_SCHED __builtin_amdgcn_sched_barrier(0)
; template <class Epi, class Sched, int KC, bool ALIGN_EPI = false, bool SP2 = false, bool ATILED = false>
; __device__ __forceinline__ void gemm_phase(LAS unsigned char* lds, const Gemm g, const Sched& S, const Epi& E, int wave_s) {
;     ...
;         for (int t = 0; t < nt; t += 2) {
;             const bool last = (t == nt - 2);
;             const char* a1 = cA + PG8_AOFF(t + 1);
;             const char* a2 = last ? nA : cA + PG8_AOFF(t + 2); const char* b2 = last ? nB : cB + (size_t)(t + 2) * kstep;
;             const char* a3 = a2 + kstep; const char* b3 = b2 + kstep;
;             if (last && has_next) S.a_ready(nxt);
;     ...
;             PG8_LDA(At, 1, 1); PG8_STAGE(PG8_SB(1, 0), b3, voffB); PG8_STAGE(PG8_SB(1, 1), b3 + hstepB, voffB); PG8_STAGE(PG8_SA(1, 0), a3, voffA);
;             PG8_WAIT_V(8); PG8_WAIT_L(0); PG8_BAR; PG8_MMA(1, 0, At, B0); PG8_MMA(1, 1, At, B1); PG8_BAR; PG8_SCHED;
	s_add_u32 s98, s28, 0x80
	s_addc_u32 s99, s29, 0
	s_add_i32 s34, s59, s38
	s_mov_b32 m0, s34
	ds_read_b128 v[198:201], v166 offset:49152
	ds_read_b128 v[202:205], v166 offset:50176
	ds_read_b128 v[206:209], v166 offset:51200
	ds_read_b128 v[210:213], v166 offset:52224
	ds_read_b128 v[214:217], v166 offset:53248
	ds_read_b128 v[218:221], v166 offset:54272
	ds_read_b128 v[222:225], v166 offset:55296
	ds_read_b128 v[226:229], v166 offset:56320
	global_load_lds_dwordx4 v134, s[98:99]
	s_add_i32 m0, s34, 0x2000
	s_add_u32 s28, s28, 0x80080
	s_addc_u32 s29, s29, 0
	s_add_i32 s34, s60, s38
	global_load_lds_dwordx4 v130, s[98:99]
	s_mov_b32 m0, s34
	s_nop 0
	global_load_lds_dwordx4 v134, s[28:29]
	s_add_i32 m0, s34, 0x2000
	s_nop 0
	global_load_lds_dwordx4 v130, s[28:29]
	s_mov_b32 m0, s48
	s_nop 0
	global_load_lds_dwordx4 v136, s[100:101]
	s_mov_b32 m0, s49
	s_nop 0
	global_load_lds_dwordx4 v132, s[100:101]
	s_waitcnt vmcnt(8)
	s_waitcnt lgkmcnt(0)
	s_barrier
	v_mfma_f32_16x16x32_bf16 v[58:61], v[152:155], v[198:201], v[58:61]
	v_mfma_f32_16x16x32_bf16 v[50:53], v[168:171], v[198:201], v[50:53]
	v_mfma_f32_16x16x32_bf16 v[42:45], v[152:155], v[206:209], v[42:45]
	s_add_i32 s57, s57, 2
	v_mfma_f32_16x16x32_bf16 v[34:37], v[168:171], v[206:209], v[34:37]
	s_add_i32 s58, s58, 0x400000
	v_mfma_f32_16x16x32_bf16 v[26:29], v[152:155], v[214:217], v[26:29]
	s_mov_b64 s[28:29], s[30:31]
	v_mfma_f32_16x16x32_bf16 v[18:21], v[168:171], v[214:217], v[18:21]
	s_add_i32 s30, s58, 0xffc00000
	v_mfma_f32_16x16x32_bf16 v[10:13], v[152:155], v[222:225], v[10:13]
	s_and_b32 s30, s30, 0x3800000
	v_mfma_f32_16x16x32_bf16 v[6:9], v[168:171], v[222:225], v[6:9]
	s_and_b32 s31, s28, 0x100
	v_mfma_f32_16x16x32_bf16 v[58:61], v[156:159], v[202:205], v[58:61]
	s_or_b32 s59, s31, s30
	v_mfma_f32_16x16x32_bf16 v[50:53], v[172:175], v[202:205], v[50:53]
	s_and_b32 s34, s58, 0x7800000
	v_mfma_f32_16x16x32_bf16 v[42:45], v[156:159], v[210:213], v[42:45]
	s_add_u32 s30, s28, 0x100
	v_mfma_f32_16x16x32_bf16 v[34:37], v[172:175], v[210:213], v[34:37]
	s_addc_u32 s31, s29, 0
	v_mfma_f32_16x16x32_bf16 v[26:29], v[156:159], v[218:221], v[26:29]
	s_and_b32 s35, s30, 0x100
	v_mfma_f32_16x16x32_bf16 v[18:21], v[172:175], v[218:221], v[18:21]
	s_or_b32 s34, s34, s35
	v_mfma_f32_16x16x32_bf16 v[10:13], v[156:159], v[226:229], v[10:13]
	s_add_u32 s34, s26, s34
	v_mfma_f32_16x16x32_bf16 v[6:9], v[172:175], v[226:229], v[6:9]
	s_addc_u32 s35, s27, 0
	v_mfma_f32_16x16x32_bf16 v[62:65], v[176:179], v[198:201], v[62:65]
	s_add_u32 s28, s55, s28
	v_mfma_f32_16x16x32_bf16 v[54:57], v[184:187], v[198:201], v[54:57]
	s_addc_u32 s29, s56, s29
	v_mfma_f32_16x16x32_bf16 v[46:49], v[176:179], v[206:209], v[46:49]
	s_add_i32 s62, 0, 0x10000
	v_mfma_f32_16x16x32_bf16 v[38:41], v[184:187], v[206:209], v[38:41]
	s_cmp_eq_u32 s57, 28
	v_mfma_f32_16x16x32_bf16 v[30:33], v[176:179], v[214:217], v[30:33]
	s_cselect_b32 s35, s19, s35
	v_mfma_f32_16x16x32_bf16 v[22:25], v[184:187], v[214:217], v[22:25]
	s_cselect_b32 s34, s53, s34
	v_mfma_f32_16x16x32_bf16 v[14:17], v[176:179], v[222:225], v[14:17]
	v_add_u32_e32 v139, s62, v163
	v_mfma_f32_16x16x32_bf16 v[2:5], v[184:187], v[222:225], v[2:5]
	s_cselect_b32 s29, s17, s29
	v_mfma_f32_16x16x32_bf16 v[62:65], v[180:183], v[202:205], v[62:65]
	s_cselect_b32 s28, s54, s28
	v_mfma_f32_16x16x32_bf16 v[54:57], v[188:191], v[202:205], v[54:57]
	s_add_i32 s63, 0, 0x14000
	v_mfma_f32_16x16x32_bf16 v[46:49], v[180:183], v[210:213], v[46:49]
	v_mfma_f32_16x16x32_bf16 v[38:41], v[188:191], v[210:213], v[38:41]
	v_mfma_f32_16x16x32_bf16 v[30:33], v[180:183], v[218:221], v[30:33]
	v_mfma_f32_16x16x32_bf16 v[22:25], v[188:191], v[218:221], v[22:25]
	v_mfma_f32_16x16x32_bf16 v[14:17], v[180:183], v[226:229], v[14:17]
	v_mfma_f32_16x16x32_bf16 v[2:5], v[188:191], v[226:229], v[2:5]
	s_barrier
	s_cmp_gt_u32 s57, 29
	s_cbranch_scc0 .LrotLBB0_233
	s_and_b64 vcc, exec, s[14:15]
	s_cbranch_vccz .LBB0_236
	s_barrier

; #define PG8_STAGE(bufoff, gbase, voff) do { _Pragma("unroll") for (int _i = 0; _i < 2; ++_i) \
;         __builtin_amdgcn_global_load_lds((const unsigned*)((const char*)(gbase) + (voff)[_i]), (LAS unsigned*)(lds + (bufoff) + ldsw + _i * 8192), 16, 0, 0); } while (0)
; #define PG8_LDA(dst, b, h) do { _Pragma("unroll") for (int m = 0; m < 4; ++m) _Pragma("unroll") for (int k = 0; k < 2; ++k) dst[m][k] = *(const LAS bf16x8*)(lds + PG8_SA(b, h) + aoff + m * 2048 + k * 1024); } while (0)
; #define PG8_LDB(dst, b, h) do { _Pragma("unroll") for (int n = 0; n < 2; ++n) _Pragma("unroll") for (int k = 0; k < 2; ++k) dst[n][k] = *(const LAS bf16x8*)(lds + PG8_SB(b, h) + boff + n * 2048 + k * 1024); } while (0)
; #define PG8_MMA(ai, bj, At, Bt) do { __builtin_amdgcn_s_setprio(1); _Pragma("unroll") for (int m = 0; m < 4; ++m) _Pragma("unroll") for (int n = 0; n < 2; ++n) _Pragma("unroll") for (int k = 0; k < 2; ++k) \
;         acc[ai][bj][m][n] = __builtin_amdgcn_mfma_f32_16x16x32_bf16(Bt[n][k], At[m][k], acc[ai][bj][m][n], 0, 0, 0); __builtin_amdgcn_s_setprio(0); } while (0)
; #define PG8_WAIT_V(n) asm volatile("s_waitcnt vmcnt(" #n ")" ::: "memory")
; #define PG8_BAR __builtin_amdgcn_s_barrier()
; template <class Epi, class Sched, int KC, bool ALIGN_EPI = false, bool SP2 = false, bool ATILED = false>
; __device__ __forceinline__ void gemm_phase(LAS unsigned char* lds, const Gemm g, const Sched& S, const Epi& E, int wave_s) {
;     ...
;         for (int t = 0; t < nt; t += 2) {
;             const bool last = (t == nt - 2);
;             const char* a1 = cA + PG8_AOFF(t + 1);
;             const char* a2 = last ? nA : cA + PG8_AOFF(t + 2); const char* b2 = last ? nB : cB + (size_t)(t + 2) * kstep;
;             const char* a3 = a2 + kstep; const char* b3 = b2 + kstep;
;             if (last && has_next) S.a_ready(nxt);
;             if constexpr (SP2) {
;             PG8_LDB(B0, 0, 0); PG8_LDB(B1, 0, 1); PG8_SCHED; PG8_LDA(At, 0, 0); PG8_STAGE(PG8_SA(1, 1), a1 + hstepA, voffA);
;             PG8_WAIT_V(8); PG8_WAIT_L(0); PG8_BAR; PG8_MMA(0, 0, At, B0); PG8_MMA(0, 1, At, B1); PG8_BAR; PG8_SCHED;
;             PG8_LDA(At, 0, 1); PG8_STAGE(PG8_SB(0, 0), b2, voffB); PG8_STAGE(PG8_SB(0, 1), b2 + hstepB, voffB); PG8_STAGE(PG8_SA(0, 0), a2, voffA);
;             PG8_WAIT_V(8); PG8_WAIT_L(0); PG8_BAR; PG8_MMA(1, 0, At, B0); PG8_MMA(1, 1, At, B1); PG8_BAR; PG8_SCHED;
.LrotLBB0_430:
	ds_read_b128 v[152:155], v139
	ds_read_b128 v[160:163], v139 offset:1024
	ds_read_b128 v[174:177], v139 offset:2048
	ds_read_b128 v[178:181], v139 offset:3072
	v_add_u32_e32 v139, s71, v165
	ds_read_b128 v[182:185], v139
	ds_read_b128 v[186:189], v139 offset:1024
	ds_read_b128 v[190:193], v139 offset:2048
	ds_read_b128 v[194:197], v139 offset:3072
	s_add_u32 s67, s26, s67
	s_addc_u32 s69, s27, 0
	s_add_u32 s68, s67, 0x10080
	s_addc_u32 s69, s69, 0
	s_add_i32 m0, s25, 0xc000
	ds_read_b128 v[198:201], v173
	ds_read_b128 v[202:205], v173 offset:1024
	ds_read_b128 v[206:209], v173 offset:2048
	ds_read_b128 v[210:213], v173 offset:3072
	ds_read_b128 v[214:217], v173 offset:4096
	ds_read_b128 v[218:221], v173 offset:5120
	ds_read_b128 v[222:225], v173 offset:6144
	ds_read_b128 v[226:229], v173 offset:7168
	global_load_lds_dwordx4 v136, s[68:69]
	s_add_i32 m0, s25, 0xe000
	s_nop 0
	global_load_lds_dwordx4 v132, s[68:69]
	s_waitcnt vmcnt(8)
	s_waitcnt lgkmcnt(0)
	s_barrier
	v_mfma_f32_16x16x32_bf16 v[126:129], v[152:155], v[198:201], v[126:129]
	v_mfma_f32_16x16x32_bf16 v[122:125], v[174:177], v[198:201], v[122:125]
	v_mfma_f32_16x16x32_bf16 v[114:117], v[152:155], v[206:209], v[114:117]
	v_mfma_f32_16x16x32_bf16 v[106:109], v[174:177], v[206:209], v[106:109]
	v_mfma_f32_16x16x32_bf16 v[98:101], v[152:155], v[214:217], v[98:101]
	v_mfma_f32_16x16x32_bf16 v[90:93], v[174:177], v[214:217], v[90:93]
	v_mfma_f32_16x16x32_bf16 v[82:85], v[152:155], v[222:225], v[82:85]
	v_mfma_f32_16x16x32_bf16 v[74:77], v[174:177], v[222:225], v[74:77]
	v_mfma_f32_16x16x32_bf16 v[126:129], v[160:163], v[202:205], v[126:129]
	v_mfma_f32_16x16x32_bf16 v[122:125], v[178:181], v[202:205], v[122:125]
	v_mfma_f32_16x16x32_bf16 v[114:117], v[160:163], v[210:213], v[114:117]
	v_mfma_f32_16x16x32_bf16 v[106:109], v[178:181], v[210:213], v[106:109]
	v_mfma_f32_16x16x32_bf16 v[98:101], v[160:163], v[218:221], v[98:101]
	v_mfma_f32_16x16x32_bf16 v[90:93], v[178:181], v[218:221], v[90:93]
	v_mfma_f32_16x16x32_bf16 v[82:85], v[160:163], v[226:229], v[82:85]
	v_mfma_f32_16x16x32_bf16 v[74:77], v[178:181], v[226:229], v[74:77]
	v_mfma_f32_16x16x32_bf16 v[118:121], v[182:185], v[198:201], v[118:121]
	v_mfma_f32_16x16x32_bf16 v[110:113], v[190:193], v[198:201], v[110:113]
	v_mfma_f32_16x16x32_bf16 v[102:105], v[182:185], v[206:209], v[102:105]
	v_mfma_f32_16x16x32_bf16 v[94:97], v[190:193], v[206:209], v[94:97]
	v_mfma_f32_16x16x32_bf16 v[86:89], v[182:185], v[214:217], v[86:89]
	v_mfma_f32_16x16x32_bf16 v[78:81], v[190:193], v[214:217], v[78:81]
	v_mfma_f32_16x16x32_bf16 v[70:73], v[182:185], v[222:225], v[70:73]
	v_mfma_f32_16x16x32_bf16 v[66:69], v[190:193], v[222:225], v[66:69]
	v_mfma_f32_16x16x32_bf16 v[118:121], v[186:189], v[202:205], v[118:121]
	v_mfma_f32_16x16x32_bf16 v[110:113], v[194:197], v[202:205], v[110:113]
	v_mfma_f32_16x16x32_bf16 v[102:105], v[186:189], v[210:213], v[102:105]
	v_mfma_f32_16x16x32_bf16 v[94:97], v[194:197], v[210:213], v[94:97]
	v_mfma_f32_16x16x32_bf16 v[86:89], v[186:189], v[218:221], v[86:89]
	v_mfma_f32_16x16x32_bf16 v[78:81], v[194:197], v[218:221], v[78:81]
	v_mfma_f32_16x16x32_bf16 v[70:73], v[186:189], v[226:229], v[70:73]
	v_mfma_f32_16x16x32_bf16 v[66:69], v[194:197], v[226:229], v[66:69]
	s_barrier
	s_add_u32 s100, s34, 0x80
	s_addc_u32 s101, s35, 0
	s_add_i32 s67, s70, s41
	s_mov_b32 m0, s67
	ds_read_b128 v[198:201], v173 offset:16384
	ds_read_b128 v[202:205], v173 offset:17408
	ds_read_b128 v[206:209], v173 offset:18432
	ds_read_b128 v[210:213], v173 offset:19456
	ds_read_b128 v[214:217], v173 offset:20480
	ds_read_b128 v[218:221], v173 offset:21504
	ds_read_b128 v[222:225], v173 offset:22528
	ds_read_b128 v[226:229], v173 offset:23552
	global_load_lds_dwordx4 v134, s[28:29]
	s_add_i32 m0, s67, 0x2000
	s_add_u32 s68, s28, 0x80000
	s_addc_u32 s69, s29, 0
	s_add_i32 s67, s71, s41
	global_load_lds_dwordx4 v130, s[28:29]
	s_mov_b32 m0, s67
	s_nop 0
	global_load_lds_dwordx4 v134, s[68:69]
	s_add_i32 m0, s67, 0x2000
	s_nop 0
	global_load_lds_dwordx4 v130, s[68:69]
	s_mov_b32 m0, s25
	s_nop 0
	global_load_lds_dwordx4 v136, s[34:35]
	s_mov_b32 m0, s52
	s_nop 0
	global_load_lds_dwordx4 v132, s[34:35]
	s_waitcnt vmcnt(8)
	s_waitcnt lgkmcnt(0)
	s_barrier
	v_mfma_f32_16x16x32_bf16 v[62:65], v[152:155], v[198:201], v[62:65]
	v_mfma_f32_16x16x32_bf16 v[58:61], v[174:177], v[198:201], v[58:61]
	v_mfma_f32_16x16x32_bf16 v[50:53], v[152:155], v[206:209], v[50:53]
	v_mfma_f32_16x16x32_bf16 v[42:45], v[174:177], v[206:209], v[42:45]
	v_mfma_f32_16x16x32_bf16 v[34:37], v[152:155], v[214:217], v[34:37]
	v_mfma_f32_16x16x32_bf16 v[26:29], v[174:177], v[214:217], v[26:29]
	v_mfma_f32_16x16x32_bf16 v[18:21], v[152:155], v[222:225], v[18:21]
	v_mfma_f32_16x16x32_bf16 v[10:13], v[174:177], v[222:225], v[10:13]
	v_mfma_f32_16x16x32_bf16 v[62:65], v[160:163], v[202:205], v[62:65]
	v_mfma_f32_16x16x32_bf16 v[58:61], v[178:181], v[202:205], v[58:61]
	v_mfma_f32_16x16x32_bf16 v[50:53], v[160:163], v[210:213], v[50:53]
	v_mfma_f32_16x16x32_bf16 v[42:45], v[178:181], v[210:213], v[42:45]
	v_mfma_f32_16x16x32_bf16 v[34:37], v[160:163], v[218:221], v[34:37]
	v_mfma_f32_16x16x32_bf16 v[26:29], v[178:181], v[218:221], v[26:29]
	v_mfma_f32_16x16x32_bf16 v[18:21], v[160:163], v[226:229], v[18:21]
	v_mfma_f32_16x16x32_bf16 v[10:13], v[178:181], v[226:229], v[10:13]
	v_mfma_f32_16x16x32_bf16 v[54:57], v[182:185], v[198:201], v[54:57]
	v_mfma_f32_16x16x32_bf16 v[46:49], v[190:193], v[198:201], v[46:49]
	v_mfma_f32_16x16x32_bf16 v[38:41], v[182:185], v[206:209], v[38:41]
	v_mfma_f32_16x16x32_bf16 v[30:33], v[190:193], v[206:209], v[30:33]
	v_mfma_f32_16x16x32_bf16 v[22:25], v[182:185], v[214:217], v[22:25]
	v_mfma_f32_16x16x32_bf16 v[14:17], v[190:193], v[214:217], v[14:17]
	v_mfma_f32_16x16x32_bf16 v[6:9], v[182:185], v[222:225], v[6:9]
	v_mfma_f32_16x16x32_bf16 v[2:5], v[190:193], v[222:225], v[2:5]
	v_mfma_f32_16x16x32_bf16 v[54:57], v[186:189], v[202:205], v[54:57]
	v_mfma_f32_16x16x32_bf16 v[46:49], v[194:197], v[202:205], v[46:49]
	v_mfma_f32_16x16x32_bf16 v[38:41], v[186:189], v[210:213], v[38:41]
	v_mfma_f32_16x16x32_bf16 v[30:33], v[194:197], v[210:213], v[30:33]
	v_mfma_f32_16x16x32_bf16 v[22:25], v[186:189], v[218:221], v[22:25]
	v_mfma_f32_16x16x32_bf16 v[14:17], v[194:197], v[218:221], v[14:17]
	v_mfma_f32_16x16x32_bf16 v[6:9], v[186:189], v[226:229], v[6:9]
	v_mfma_f32_16x16x32_bf16 v[2:5], v[194:197], v[226:229], v[2:5]
	s_barrier
; #define PG8_STAGE(bufoff, gbase, voff) do { _Pragma("unroll") for (int _i = 0; _i < 2; ++_i) \
;         __builtin_amdgcn_global_load_lds((const unsigned*)((const char*)(gbase) + (voff)[_i]), (LAS unsigned*)(lds + (bufoff) + ldsw + _i * 8192), 16, 0, 0); } while (0)
; #define PG8_LDA(dst, b, h) do { _Pragma("unroll") for (int m = 0; m < 4; ++m) _Pragma("unroll") for (int k = 0; k < 2; ++k) dst[m][k] = *(const LAS bf16x8*)(lds + PG8_SA(b, h) + aoff + m * 2048 + k * 1024); } while (0)
; #define PG8_LDB(dst, b, h) do { _Pragma("unroll") for (int n = 0; n < 2; ++n) _Pragma("unroll") for (int k = 0; k < 2; ++k) dst[n][k] = *(const LAS bf16x8*)(lds + PG8_SB(b, h) + boff + n * 2048 + k * 1024); } while (0)
; #define PG8_MMA(ai, bj, At, Bt) do { __builtin_amdgcn_s_setprio(1); _Pragma("unroll") for (int m = 0; m < 4; ++m) _Pragma("unroll") for (int n = 0; n < 2; ++n) _Pragma("unroll") for (int k = 0; k < 2; ++k) \
;         acc[ai][bj][m][n] = __builtin_amdgcn_mfma_f32_16x16x32_bf16(Bt[n][k], At[m][k], acc[ai][bj][m][n], 0, 0, 0); __builtin_amdgcn_s_setprio(0); } while (0)
; #define PG8_WAIT_V(n) asm volatile("s_waitcnt vmcnt(" #n ")" ::: "memory")
; #define PG8_WAIT_L(n) asm volatile("s_waitcnt lgkmcnt(" #n ")" ::: "memory")
; #define PG8_BAR __builtin_amdgcn_s_barrier()
; #define PG8_SCHED __builtin_amdgcn_sched_barrier(0)
; template <class Epi, class Sched, int KC, bool ALIGN_EPI = false, bool SP2 = false, bool ATILED = false>
; __device__ __forceinline__ void gemm_phase(LAS unsigned char* lds, const Gemm g, const Sched& S, const Epi& E, int wave_s) {
;     ...
;             PG8_LDB(B0, 1, 0); PG8_LDB(B1, 1, 1); PG8_SCHED; PG8_LDA(At, 1, 0); PG8_STAGE(PG8_SA(0, 1), a2 + hstepA, voffA);
;             PG8_WAIT_V(8); PG8_WAIT_L(0); PG8_BAR; PG8_MMA(0, 0, At, B0); PG8_MMA(0, 1, At, B1); PG8_BAR; PG8_SCHED;
	s_add_i32 s67, 0, 0x18000
	v_add_u32_e32 v139, s67, v165
	s_add_i32 s68, 0, 0x1c000
	ds_read_b128 v[152:155], v139
	ds_read_b128 v[160:163], v139 offset:1024
	ds_read_b128 v[174:177], v139 offset:2048
	ds_read_b128 v[178:181], v139 offset:3072
	v_add_u32_e32 v139, s68, v165
	ds_read_b128 v[182:185], v139
	ds_read_b128 v[186:189], v139 offset:1024
	ds_read_b128 v[190:193], v139 offset:2048
	ds_read_b128 v[194:197], v139 offset:3072
	s_add_u32 s34, s34, 0x10000
	s_addc_u32 s35, s35, 0
	s_mov_b32 m0, s53
	ds_read_b128 v[198:201], v173 offset:32768
	ds_read_b128 v[202:205], v173 offset:33792
	ds_read_b128 v[206:209], v173 offset:34816
	ds_read_b128 v[210:213], v173 offset:35840
	ds_read_b128 v[214:217], v173 offset:36864
	ds_read_b128 v[218:221], v173 offset:37888
	ds_read_b128 v[222:225], v173 offset:38912
	ds_read_b128 v[226:229], v173 offset:39936
	global_load_lds_dwordx4 v136, s[34:35]
	s_mov_b32 m0, s54
	s_nop 0
	global_load_lds_dwordx4 v132, s[34:35]
	s_waitcnt vmcnt(8)
	s_waitcnt lgkmcnt(0)
	s_barrier
	v_mfma_f32_16x16x32_bf16 v[126:129], v[152:155], v[198:201], v[126:129]
	v_mfma_f32_16x16x32_bf16 v[122:125], v[174:177], v[198:201], v[122:125]
	v_mfma_f32_16x16x32_bf16 v[114:117], v[152:155], v[206:209], v[114:117]
	v_mfma_f32_16x16x32_bf16 v[106:109], v[174:177], v[206:209], v[106:109]
	v_mfma_f32_16x16x32_bf16 v[98:101], v[152:155], v[214:217], v[98:101]
	v_mfma_f32_16x16x32_bf16 v[90:93], v[174:177], v[214:217], v[90:93]
	v_mfma_f32_16x16x32_bf16 v[82:85], v[152:155], v[222:225], v[82:85]
	v_mfma_f32_16x16x32_bf16 v[74:77], v[174:177], v[222:225], v[74:77]
	v_mfma_f32_16x16x32_bf16 v[126:129], v[160:163], v[202:205], v[126:129]
	v_mfma_f32_16x16x32_bf16 v[122:125], v[178:181], v[202:205], v[122:125]
	v_mfma_f32_16x16x32_bf16 v[114:117], v[160:163], v[210:213], v[114:117]
	v_mfma_f32_16x16x32_bf16 v[106:109], v[178:181], v[210:213], v[106:109]
	v_mfma_f32_16x16x32_bf16 v[98:101], v[160:163], v[218:221], v[98:101]
	v_mfma_f32_16x16x32_bf16 v[90:93], v[178:181], v[218:221], v[90:93]
	v_mfma_f32_16x16x32_bf16 v[82:85], v[160:163], v[226:229], v[82:85]
	v_mfma_f32_16x16x32_bf16 v[74:77], v[178:181], v[226:229], v[74:77]
	v_mfma_f32_16x16x32_bf16 v[118:121], v[182:185], v[198:201], v[118:121]
	v_mfma_f32_16x16x32_bf16 v[110:113], v[190:193], v[198:201], v[110:113]
	v_mfma_f32_16x16x32_bf16 v[102:105], v[182:185], v[206:209], v[102:105]
	v_mfma_f32_16x16x32_bf16 v[94:97], v[190:193], v[206:209], v[94:97]
	v_mfma_f32_16x16x32_bf16 v[86:89], v[182:185], v[214:217], v[86:89]
	v_mfma_f32_16x16x32_bf16 v[78:81], v[190:193], v[214:217], v[78:81]
	v_mfma_f32_16x16x32_bf16 v[70:73], v[182:185], v[222:225], v[70:73]
	v_mfma_f32_16x16x32_bf16 v[66:69], v[190:193], v[222:225], v[66:69]
	v_mfma_f32_16x16x32_bf16 v[118:121], v[186:189], v[202:205], v[118:121]
	v_mfma_f32_16x16x32_bf16 v[110:113], v[194:197], v[202:205], v[110:113]
	v_mfma_f32_16x16x32_bf16 v[102:105], v[186:189], v[210:213], v[102:105]
	v_mfma_f32_16x16x32_bf16 v[94:97], v[194:197], v[210:213], v[94:97]
	v_mfma_f32_16x16x32_bf16 v[86:89], v[186:189], v[218:221], v[86:89]
	v_mfma_f32_16x16x32_bf16 v[78:81], v[194:197], v[218:221], v[78:81]
	v_mfma_f32_16x16x32_bf16 v[70:73], v[186:189], v[226:229], v[70:73]
	v_mfma_f32_16x16x32_bf16 v[66:69], v[194:197], v[226:229], v[66:69]
	s_barrier
; #define PG8_STAGE(bufoff, gbase, voff) do { _Pragma("unroll") for (int _i = 0; _i < 2; ++_i) \
;         __builtin_amdgcn_global_load_lds((const unsigned*)((const char*)(gbase) + (voff)[_i]), (LAS unsigned*)(lds + (bufoff) + ldsw + _i * 8192), 16, 0, 0); } while (0)
; #define PG8_LDA(dst, b, h) do { _Pragma("unroll") for (int m = 0; m < 4; ++m) _Pragma("unroll") for (int k = 0; k < 2; ++k) dst[m][k] = *(const LAS bf16x8*)(lds + PG8_SA(b, h) + aoff + m * 2048 + k * 1024); } while (0)
; #define PG8_MMA(ai, bj, At, Bt) do { __builtin_amdgcn_s_setprio(1); _Pragma("unroll") for (int m = 0; m < 4; ++m) _Pragma("unroll") for (int n = 0; n < 2; ++n) _Pragma("unroll") for (int k = 0; k < 2; ++k) \
;         acc[ai][bj][m][n] = __builtin_amdgcn_mfma_f32_16x16x32_bf16(Bt[n][k], At[m][k], acc[ai][bj][m][n], 0, 0, 0); __builtin_amdgcn_s_setprio(0); } while (0)
; #define PG8_WAIT_V(n) asm volatile("s_waitcnt vmcnt(" #n ")" ::: "memory")
; #define PG8_WAIT_L(n) asm volatile("s_waitcnt lgkmcnt(" #n ")" ::: "memory")
; #define PG8_BAR __builtin_amdgcn_s_barrier()
; #define PG8_SCHED __builtin_amdgcn_sched_barrier(0)
; template <class Epi, class Sched, int KC, bool ALIGN_EPI = false, bool SP2 = false, bool ATILED = false>
; __device__ __forceinline__ void gemm_phase(LAS unsigned char* lds, const Gemm g, const Sched& S, const Epi& E, int wave_s) {
;     ...
;         for (int t = 0; t < nt; t += 2) {
;             const bool last = (t == nt - 2);
;             const char* a1 = cA + PG8_AOFF(t + 1);
;             const char* a2 = last ? nA : cA + PG8_AOFF(t + 2); const char* b2 = last ? nB : cB + (size_t)(t + 2) * kstep;
;             const char* a3 = a2 + kstep; const char* b3 = b2 + kstep;
;             if (last && has_next) S.a_ready(nxt);
;     ...
;             PG8_LDA(At, 1, 1); PG8_STAGE(PG8_SB(1, 0), b3, voffB); PG8_STAGE(PG8_SB(1, 1), b3 + hstepB, voffB); PG8_STAGE(PG8_SA(1, 0), a3, voffA);
;             PG8_WAIT_V(8); PG8_WAIT_L(0); PG8_BAR; PG8_MMA(1, 0, At, B0); PG8_MMA(1, 1, At, B1); PG8_BAR; PG8_SCHED;
	s_add_u32 s98, s28, 0x80
	s_addc_u32 s99, s29, 0
	s_add_i32 s34, s67, s41
	s_mov_b32 m0, s34
	ds_read_b128 v[198:201], v173 offset:49152
	ds_read_b128 v[202:205], v173 offset:50176
	ds_read_b128 v[206:209], v173 offset:51200
	ds_read_b128 v[210:213], v173 offset:52224
	ds_read_b128 v[214:217], v173 offset:53248
	ds_read_b128 v[218:221], v173 offset:54272
	ds_read_b128 v[222:225], v173 offset:55296
	ds_read_b128 v[226:229], v173 offset:56320
	global_load_lds_dwordx4 v134, s[98:99]
	s_add_i32 m0, s34, 0x2000
	s_add_u32 s28, s28, 0x80080
	s_addc_u32 s29, s29, 0
	s_add_i32 s34, s68, s41
	global_load_lds_dwordx4 v130, s[98:99]
	s_mov_b32 m0, s34
	s_nop 0
	global_load_lds_dwordx4 v134, s[28:29]
	s_add_i32 m0, s34, 0x2000
	s_nop 0
	global_load_lds_dwordx4 v130, s[28:29]
	s_mov_b32 m0, s55
	s_nop 0
	global_load_lds_dwordx4 v136, s[100:101]
	s_mov_b32 m0, s56
	s_nop 0
	global_load_lds_dwordx4 v132, s[100:101]
	s_waitcnt vmcnt(8)
	s_waitcnt lgkmcnt(0)
	s_barrier
	v_mfma_f32_16x16x32_bf16 v[62:65], v[152:155], v[198:201], v[62:65]
	v_mfma_f32_16x16x32_bf16 v[58:61], v[174:177], v[198:201], v[58:61]
	v_mfma_f32_16x16x32_bf16 v[50:53], v[152:155], v[206:209], v[50:53]
	s_add_i32 s65, s65, 2
	v_mfma_f32_16x16x32_bf16 v[42:45], v[174:177], v[206:209], v[42:45]
	s_add_i32 s66, s66, 0x400000
	v_mfma_f32_16x16x32_bf16 v[34:37], v[152:155], v[214:217], v[34:37]
	s_mov_b64 s[28:29], s[30:31]
	v_mfma_f32_16x16x32_bf16 v[26:29], v[174:177], v[214:217], v[26:29]
	s_add_i32 s30, s66, 0xffc00000
	v_mfma_f32_16x16x32_bf16 v[18:21], v[152:155], v[222:225], v[18:21]
	s_and_b32 s30, s30, 0x3800000
	v_mfma_f32_16x16x32_bf16 v[10:13], v[174:177], v[222:225], v[10:13]
	s_and_b32 s31, s28, 0x100
	v_mfma_f32_16x16x32_bf16 v[62:65], v[160:163], v[202:205], v[62:65]
	s_or_b32 s67, s31, s30
	v_mfma_f32_16x16x32_bf16 v[58:61], v[178:181], v[202:205], v[58:61]
	s_and_b32 s34, s66, 0x7800000
	v_mfma_f32_16x16x32_bf16 v[50:53], v[160:163], v[210:213], v[50:53]
	s_add_u32 s30, s28, 0x100
	v_mfma_f32_16x16x32_bf16 v[42:45], v[178:181], v[210:213], v[42:45]
	s_addc_u32 s31, s29, 0
	v_mfma_f32_16x16x32_bf16 v[34:37], v[160:163], v[218:221], v[34:37]
	s_and_b32 s35, s30, 0x100
	v_mfma_f32_16x16x32_bf16 v[26:29], v[178:181], v[218:221], v[26:29]
	s_or_b32 s34, s34, s35
	v_mfma_f32_16x16x32_bf16 v[18:21], v[160:163], v[226:229], v[18:21]
	s_add_u32 s34, s26, s34
	v_mfma_f32_16x16x32_bf16 v[10:13], v[178:181], v[226:229], v[10:13]
	s_addc_u32 s35, s27, 0
	v_mfma_f32_16x16x32_bf16 v[54:57], v[182:185], v[198:201], v[54:57]
	s_add_u32 s28, s63, s28
	v_mfma_f32_16x16x32_bf16 v[46:49], v[190:193], v[198:201], v[46:49]
	s_addc_u32 s29, s64, s29
	v_mfma_f32_16x16x32_bf16 v[38:41], v[182:185], v[206:209], v[38:41]
	s_add_i32 s70, 0, 0x10000
	v_mfma_f32_16x16x32_bf16 v[30:33], v[190:193], v[206:209], v[30:33]
	s_cmp_eq_u32 s65, 28
	v_mfma_f32_16x16x32_bf16 v[22:25], v[182:185], v[214:217], v[22:25]
	s_cselect_b32 s35, s19, s35
	v_mfma_f32_16x16x32_bf16 v[14:17], v[190:193], v[214:217], v[14:17]
	s_cselect_b32 s34, s61, s34
	v_mfma_f32_16x16x32_bf16 v[6:9], v[182:185], v[222:225], v[6:9]
	v_add_u32_e32 v139, s70, v165
	v_mfma_f32_16x16x32_bf16 v[2:5], v[190:193], v[222:225], v[2:5]
	s_cselect_b32 s29, s17, s29
	v_mfma_f32_16x16x32_bf16 v[54:57], v[186:189], v[202:205], v[54:57]
	s_cselect_b32 s28, s62, s28
	v_mfma_f32_16x16x32_bf16 v[46:49], v[194:197], v[202:205], v[46:49]
	s_add_i32 s71, 0, 0x14000
	v_mfma_f32_16x16x32_bf16 v[38:41], v[186:189], v[210:213], v[38:41]
	v_mfma_f32_16x16x32_bf16 v[30:33], v[194:197], v[210:213], v[30:33]
	v_mfma_f32_16x16x32_bf16 v[22:25], v[186:189], v[218:221], v[22:25]
	v_mfma_f32_16x16x32_bf16 v[14:17], v[194:197], v[218:221], v[14:17]
	v_mfma_f32_16x16x32_bf16 v[6:9], v[186:189], v[226:229], v[6:9]
	v_mfma_f32_16x16x32_bf16 v[2:5], v[194:197], v[226:229], v[2:5]
	s_barrier
	s_cmp_gt_u32 s65, 29
	s_cbranch_scc0 .LrotLBB0_430
	s_and_b64 vcc, exec, s[14:15]
	s_cbranch_vccz .LBB0_433
	s_barrier
